# P0 outputs (XN rows, dt_raw, rinv, w_in transpose) stored write-through (sc1) so the grid barrier behind P0 has no dirty L2 to write back
# speedup vs baseline: 1.0028x; 1.0028x over previous
; #define LAS __attribute__((address_space(3)))
; #define LDS_WAIT() asm volatile("s_waitcnt lgkmcnt(0)" ::: "memory")
; __device__ __forceinline__ void transpose_item(const float* W, int ldw, int K, bf16* WT, LAS float* scr, int kb, int nbk, int lane) {
;     const int k0 = 64 * kb, n0 = 32 * nbk;
; #pragma unroll 8
;     for (int i = 0; i < 32; ++i) { const int kk = 2 * i + (lane >> 5); scr[kk * 33 + (lane & 31)] = W[(size_t)(k0 + kk) * ldw + n0 + (lane & 31)]; }
;     LDS_WAIT();
;     const int c = lane & 7;
; #pragma unroll
;     for (int j = 0; j < 4; ++j) { const int n = (lane >> 3) + 8 * j; const LAS float* s = scr + (8 * c) * 33 + n;
;         v4u o; o.x = pk2(s[0 * 33], s[1 * 33]); o.y = pk2(s[2 * 33], s[3 * 33]); o.z = pk2(s[4 * 33], s[5 * 33]); o.w = pk2(s[6 * 33], s[7 * 33]);
;         *(v4u*)(WT + (size_t)(n0 + n) * K + k0 + 8 * c) = o; }
;     LDS_WAIT();
; }
.LBB0_9:
	s_lshl_b32 s18, s15, 1
	s_lshl_b32 s19, s14, 1
	v_or_b32_e32 v15, s18, v3
	v_or_b32_e32 v17, s19, v20
	s_add_i32 s20, s18, 4
	s_add_i32 s21, s19, 4
	s_add_i32 s22, s18, 8
	s_add_i32 s23, s19, 8
	s_add_i32 s24, s18, 12
	s_add_i32 s25, s19, 12
	s_add_i32 s26, s18, 16
	s_add_i32 s27, s19, 16
	s_add_i32 s28, s18, 20
	s_add_i32 s29, s19, 20
	s_add_i32 s30, s18, 24
	s_add_i32 s31, s19, 24
	s_add_i32 s34, s18, 28
	s_add_i32 s35, s19, 28
	v_mad_i64_i32 v[24:25], s[16:17], v17, s11, v[18:19]
	v_mad_i64_i32 v[26:27], s[16:17], v15, s11, v[18:19]
	v_or_b32_e32 v15, s20, v3
	v_or_b32_e32 v17, s21, v20
	v_or_b32_e32 v34, s22, v3
	v_or_b32_e32 v32, s23, v20
	v_or_b32_e32 v38, s24, v3
	v_or_b32_e32 v36, s25, v20
	v_or_b32_e32 v43, s26, v3
	v_or_b32_e32 v40, s27, v20
	v_or_b32_e32 v48, s28, v3
	v_or_b32_e32 v46, s29, v20
	v_or_b32_e32 v52, s30, v3
	v_or_b32_e32 v50, s31, v20
	v_or_b32_e32 v56, s34, v3
	v_or_b32_e32 v54, s35, v20
	v_mad_i64_i32 v[28:29], s[16:17], v17, s11, v[18:19]
	v_mad_i64_i32 v[30:31], s[16:17], v15, s11, v[18:19]
	v_mad_i64_i32 v[32:33], s[16:17], v32, s11, v[18:19]
	v_mad_i64_i32 v[34:35], s[16:17], v34, s11, v[18:19]
	v_mad_i64_i32 v[36:37], s[16:17], v36, s11, v[18:19]
	v_mad_i64_i32 v[38:39], s[16:17], v38, s11, v[18:19]
	v_mad_i64_i32 v[40:41], s[16:17], v40, s11, v[18:19]
	v_mad_i64_i32 v[44:45], s[16:17], v43, s11, v[18:19]
	v_mad_i64_i32 v[46:47], s[16:17], v46, s11, v[18:19]
	v_mad_i64_i32 v[48:49], s[16:17], v48, s11, v[18:19]
	v_mad_i64_i32 v[50:51], s[16:17], v50, s11, v[18:19]
	v_mad_i64_i32 v[52:53], s[16:17], v52, s11, v[18:19]
	v_mad_i64_i32 v[54:55], s[16:17], v54, s11, v[18:19]
	v_mad_i64_i32 v[56:57], s[16:17], v56, s11, v[18:19]
	global_load_dword v15, v[24:25], off
	global_load_dword v17, v[26:27], off
	global_load_dword v43, v[28:29], off
	global_load_dword v58, v[30:31], off
	global_load_dword v59, v[32:33], off
	global_load_dword v60, v[34:35], off
	global_load_dword v61, v[36:37], off
	global_load_dword v62, v[38:39], off
	global_load_dword v63, v[40:41], off
	global_load_dword v64, v[44:45], off
	global_load_dword v65, v[46:47], off
	global_load_dword v66, v[48:49], off
	global_load_dword v67, v[50:51], off
	global_load_dword v68, v[52:53], off
	global_load_dword v69, v[54:55], off
	global_load_dword v70, v[56:57], off
	v_or_b32_e32 v26, s18, v1
	v_or_b32_e32 v24, s19, v6
	s_add_i32 s14, s14, 16
	s_add_i32 s15, s15, 16
	s_add_i32 s13, s13, -16
	v_mad_u64_u32 v[24:25], s[16:17], v24, s3, v[10:11]
	v_mad_u64_u32 v[26:27], s[16:17], v26, s3, v[10:11]
	v_or_b32_e32 v25, s20, v1
	v_or_b32_e32 v27, s21, v6
	v_or_b32_e32 v34, s22, v1
	v_or_b32_e32 v32, s23, v6
	v_or_b32_e32 v38, s24, v1
	v_or_b32_e32 v36, s25, v6
	v_or_b32_e32 v44, s26, v1
	v_or_b32_e32 v40, s27, v6
	v_or_b32_e32 v48, s28, v1
	v_or_b32_e32 v46, s29, v6
	v_or_b32_e32 v52, s30, v1
	v_or_b32_e32 v50, s31, v6
	v_or_b32_e32 v56, s34, v1
	v_or_b32_e32 v54, s35, v6
	s_cmp_lg_u32 s13, 0
	v_mad_u64_u32 v[28:29], s[16:17], v27, s3, v[10:11]
	v_mad_u64_u32 v[30:31], s[16:17], v25, s3, v[10:11]
	v_mad_u64_u32 v[32:33], s[16:17], v32, s3, v[10:11]
	v_mad_u64_u32 v[34:35], s[16:17], v34, s3, v[10:11]
	v_mad_u64_u32 v[36:37], s[16:17], v36, s3, v[10:11]
	v_mad_u64_u32 v[38:39], s[16:17], v38, s3, v[10:11]
	v_mad_u64_u32 v[40:41], s[16:17], v40, s3, v[10:11]
	v_mad_u64_u32 v[44:45], s[16:17], v44, s3, v[10:11]
	v_mad_u64_u32 v[46:47], s[16:17], v46, s3, v[10:11]
	v_mad_u64_u32 v[48:49], s[16:17], v48, s3, v[10:11]
	v_mad_u64_u32 v[50:51], s[16:17], v50, s3, v[10:11]
	v_mad_u64_u32 v[52:53], s[16:17], v52, s3, v[10:11]
	v_mad_u64_u32 v[54:55], s[16:17], v54, s3, v[10:11]
	v_mad_u64_u32 v[56:57], s[16:17], v56, s3, v[10:11]
	s_waitcnt vmcnt(15)
	ds_write_b32 v24, v15
	s_waitcnt vmcnt(14)
	ds_write_b32 v26, v17
	s_waitcnt vmcnt(13)
	ds_write_b32 v28, v43
	s_waitcnt vmcnt(12)
	ds_write_b32 v30, v58
	s_waitcnt vmcnt(11)
	ds_write_b32 v32, v59
	s_waitcnt vmcnt(10)
	ds_write_b32 v34, v60
	s_waitcnt vmcnt(9)
	ds_write_b32 v36, v61
	s_waitcnt vmcnt(8)
	ds_write_b32 v38, v62
	s_waitcnt vmcnt(7)
	ds_write_b32 v40, v63
	s_waitcnt vmcnt(6)
	ds_write_b32 v44, v64
	s_waitcnt vmcnt(5)
	ds_write_b32 v46, v65
	s_waitcnt vmcnt(4)
	ds_write_b32 v48, v66
	s_waitcnt vmcnt(3)
	ds_write_b32 v50, v67
	s_waitcnt vmcnt(2)
	ds_write_b32 v52, v68
	s_waitcnt vmcnt(1)
	ds_write_b32 v54, v69
	s_waitcnt vmcnt(0)
	ds_write_b32 v56, v70
	s_cbranch_scc1 .LBB0_9
	s_waitcnt lgkmcnt(0)
	ds_read2_b32 v[24:25], v7 offset0:33 offset1:41
	ds_read2_b32 v[26:27], v7 offset1:8
	ds_read2_b32 v[28:29], v7 offset0:66 offset1:74
	ds_read2_b32 v[30:31], v7 offset0:99 offset1:107
	ds_read2_b32 v[32:33], v7 offset0:132 offset1:140
	ds_read2_b32 v[34:35], v7 offset0:165 offset1:173
	ds_read2_b32 v[36:37], v7 offset0:198 offset1:206
	ds_read2_b32 v[38:39], v7 offset0:231 offset1:239
	v_or_b32_e32 v44, v14, v5
	v_ashrrev_i32_e32 v17, 31, v16
	v_ashrrev_i32_e32 v45, 31, v44
	v_lshl_add_u64 v[40:41], v[16:17], 1, v[12:13]
	v_lshlrev_b64 v[44:45], 11, v[44:45]
	s_waitcnt lgkmcnt(6)
	v_cvt_pk_bf16_f32 v16, v26, v24
	s_waitcnt lgkmcnt(4)
	v_cvt_pk_bf16_f32 v17, v28, v30
	s_waitcnt lgkmcnt(2)
	v_cvt_pk_bf16_f32 v18, v32, v34
	s_waitcnt lgkmcnt(0)
	v_cvt_pk_bf16_f32 v19, v36, v38
	v_lshl_add_u64 v[44:45], v[40:41], 0, v[44:45]
	v_or_b32_e32 v24, v14, v11
	global_store_dwordx4 v[44:45], v[16:19], off sc1
	v_add_u32_e32 v23, s8, v23
	v_cmp_lt_i32_e32 vcc, s12, v23
	v_cvt_pk_bf16_f32 v16, v27, v25
	v_ashrrev_i32_e32 v25, 31, v24
	v_cvt_pk_bf16_f32 v17, v29, v31
	v_cvt_pk_bf16_f32 v18, v33, v35
	v_cvt_pk_bf16_f32 v19, v37, v39
	v_lshlrev_b64 v[24:25], 11, v[24:25]
	ds_read2_b32 v[26:27], v7 offset0:49 offset1:57
	ds_read2_b32 v[28:29], v7 offset0:16 offset1:24
	ds_read2_b32 v[30:31], v7 offset0:82 offset1:90
	ds_read2_b32 v[32:33], v7 offset0:115 offset1:123
	ds_read2_b32 v[34:35], v7 offset0:148 offset1:156
	ds_read2_b32 v[36:37], v7 offset0:181 offset1:189
	ds_read2_b32 v[38:39], v7 offset0:214 offset1:222
	ds_read2_b32 v[44:45], v7 offset0:247 offset1:255
	v_lshl_add_u64 v[24:25], v[40:41], 0, v[24:25]
	global_store_dwordx4 v[24:25], v[16:19], off sc1
	v_or_b32_e32 v24, v14, v21
	v_ashrrev_i32_e32 v25, 31, v24
	v_or_b32_e32 v14, v14, v22
	v_lshlrev_b64 v[24:25], 11, v[24:25]
	v_ashrrev_i32_e32 v15, 31, v14
	s_waitcnt lgkmcnt(6)
	v_cvt_pk_bf16_f32 v16, v28, v26
	s_waitcnt lgkmcnt(4)
	v_cvt_pk_bf16_f32 v17, v30, v32
	s_waitcnt lgkmcnt(2)
	v_cvt_pk_bf16_f32 v18, v34, v36
	s_waitcnt lgkmcnt(0)
	v_cvt_pk_bf16_f32 v19, v38, v44
	v_lshl_add_u64 v[24:25], v[40:41], 0, v[24:25]
	v_lshlrev_b64 v[14:15], 11, v[14:15]
	global_store_dwordx4 v[24:25], v[16:19], off sc1
	v_lshl_add_u64 v[14:15], v[40:41], 0, v[14:15]
	s_or_b64 s[4:5], vcc, s[4:5]
	v_cvt_pk_bf16_f32 v16, v29, v27
	v_cvt_pk_bf16_f32 v17, v31, v33
	v_cvt_pk_bf16_f32 v18, v35, v37
	v_cvt_pk_bf16_f32 v19, v39, v45
	global_store_dwordx4 v[14:15], v[16:19], off sc1
	s_waitcnt lgkmcnt(0)
	s_andn2_b64 exec, exec, s[4:5]
	s_cbranch_execnz .LBB0_8

; #define LAS __attribute__((address_space(3)))
; template <int MODE  > ...
;     ...
;     for (int row = gwave; row < T; row += nwaves) {
;         const float4* xr = (const float4*)(in + (size_t)row * D) + lane; const uint2* xb = (const uint2*)((const bf16*)in + (size_t)row * D) + lane;
;         float4 v[4]; float ss = 0.f;
; #pragma unroll
;         for (int j = 0; j < 4; ++j) {
;             if (MODE == 2) { const uint2 w = xb[64 * j]; v[j] = make_float4(__uint_as_float(w.x << 16), __uint_as_float(w.x & 0xffff0000u), __uint_as_float(w.y << 16), __uint_as_float(w.y & 0xffff0000u)); }
;             else if (MODE == 1) { typedef float f4v __attribute__((ext_vector_type(4))); const f4v t4 = __builtin_nontemporal_load((const f4v*)xr + 64 * j); v[j] = make_float4(t4.x, t4.y, t4.z, t4.w); }
;             else v[j] = xr[64 * j];
;             ss += v[j].x * v[j].x + v[j].y * v[j].y + v[j].z * v[j].z + v[j].w * v[j].w; }
;         ss = wave_sum(ss);
;         const float r = rsqrtf(ss * (1.f / D) + EPS);
;         unsigned long long* o8 = (unsigned long long*)(outp + (size_t)row * D) + lane;
;         float dacc[8]; float y[4][4]; float mx = 0.f;
; #pragma unroll
;         for (int h = 0; h < 8; ++h) dacc[h] = 0.f;
; #pragma unroll
;         for (int j = 0; j < 4; ++j) {
;             const float4 gv = ((const float4*)g)[lane + 64 * j];
;             y[j][0] = v[j].x * r * gv.x; y[j][1] = v[j].y * r * gv.y; y[j][2] = v[j].z * r * gv.z; y[j][3] = v[j].w * r * gv.w;
;             o8[64 * j] = (unsigned long long)pk2(y[j][0], y[j][1]) | ((unsigned long long)pk2(y[j][2], y[j][3]) << 32);
;             if (MODE == 2) mx = fmaxf(mx, fmaxf(fmaxf(fabsf(y[j][0]), fabsf(y[j][1])), fmaxf(fabsf(y[j][2]), fabsf(y[j][3]))));
;             if (MODE == 1) {
; #pragma unroll
;                 for (int h = 0; h < 8; ++h) {
;                     typedef float f4v __attribute__((ext_vector_type(4)));
;                     const f4v wv = *(const LAS f4v*)(ldsb + h * 16384 + 8448 + (256 * j + 4 * lane) * 4);
;                     dacc[h] += y[j][0] * wv.x + y[j][1] * wv.y + y[j][2] * wv.z + y[j][3] * wv.w;
;                 }
.LBB0_29:
	s_waitcnt vmcnt(7)
	v_mov_b32_e32 v168, v236
	v_mov_b32_e32 v169, v237
	v_mov_b32_e32 v170, v238
	v_mov_b32_e32 v171, v239
	v_mov_b32_e32 v150, v240
	v_mov_b32_e32 v151, v241
	v_mov_b32_e32 v152, v242
	v_mov_b32_e32 v153, v243
	v_mov_b32_e32 v172, v244
	v_mov_b32_e32 v173, v245
	v_mov_b32_e32 v174, v246
	v_mov_b32_e32 v175, v247
	v_mov_b32_e32 v146, v248
	v_mov_b32_e32 v147, v249
	v_mov_b32_e32 v148, v250
	v_mov_b32_e32 v149, v251
	v_add_u32_e32 v252, s8, v154
	v_cmp_lt_i32_e32 vcc, s40, v252
	v_lshl_add_u64 v[252:253], v[160:161], 0, s[18:19]
	s_nop 1
	v_cndmask_b32_e32 v252, v252, v160, vcc
	v_cndmask_b32_e32 v253, v253, v161, vcc
	global_load_dwordx4 v[236:239], v[252:253], off offset:-3072 nt
	global_load_dwordx4 v[240:243], v[252:253], off offset:-2048 nt
	global_load_dwordx4 v[244:247], v[252:253], off offset:-1024 nt
	global_load_dwordx4 v[248:251], v[252:253], off nt
	s_mov_b32 s22, 0x800000
	v_lshl_add_u64 v[164:165], s[90:91], 0, v[158:159]
	s_nop 0
	v_mov_b32_e32 v176, v169
	s_nop 0
	v_mov_b32_e32 v177, v151
	v_mov_b32_e32 v166, v168
	v_mov_b32_e32 v167, v150
	s_nop 0
	v_mov_b32_e32 v180, v173
	s_nop 0
	v_mov_b32_e32 v181, v147
	v_pk_mul_f32 v[176:177], v[176:177], v[176:177]
	v_mov_b32_e32 v178, v172
	v_mov_b32_e32 v179, v146
	v_mov_b32_e32 v182, v170
	v_mov_b32_e32 v183, v152
	v_pk_mul_f32 v[180:181], v[180:181], v[180:181]
	v_pk_fma_f32 v[166:167], v[166:167], v[166:167], v[176:177]
	v_mov_b32_e32 v184, v174
	v_mov_b32_e32 v185, v148
	v_mov_b32_e32 v186, v171
	v_mov_b32_e32 v187, v153
	v_pk_fma_f32 v[176:177], v[178:179], v[178:179], v[180:181]
	v_pk_fma_f32 v[166:167], v[182:183], v[182:183], v[166:167]
	v_mov_b32_e32 v188, v175
	v_mov_b32_e32 v189, v149
	v_pk_fma_f32 v[176:177], v[184:185], v[184:185], v[176:177]
	v_pk_fma_f32 v[166:167], v[186:187], v[186:187], v[166:167]
	v_pk_fma_f32 v[176:177], v[188:189], v[188:189], v[176:177]
	v_add_f32_e32 v155, v166, v167
	v_add_f32_e32 v155, v155, v176
	v_add_f32_e32 v155, v155, v177
	s_nop 1
	v_add_f32_dpp v155, v155, v155 quad_perm:[1,0,3,2] row_mask:0xf bank_mask:0xf bound_ctrl:1
	s_nop 1
	v_add_f32_dpp v155, v155, v155 quad_perm:[2,3,0,1] row_mask:0xf bank_mask:0xf bound_ctrl:1
	s_nop 1
	v_add_f32_dpp v155, v155, v155 row_half_mirror row_mask:0xf bank_mask:0xf bound_ctrl:1
	s_nop 1
	v_add_f32_dpp v155, v155, v155 row_mirror row_mask:0xf bank_mask:0xf bound_ctrl:1
	s_nop 0
	v_readlane_b32 s23, v155, 16
	v_readlane_b32 s24, v155, 48
	v_readlane_b32 s0, v155, 0
	v_readlane_b32 s1, v155, 32
	v_mov_b32_e32 v166, s23
	v_mov_b32_e32 v167, s24
	v_pk_add_f32 v[166:167], s[0:1], v[166:167]
	s_nop 0
	v_add_f32_e32 v155, v166, v167
	v_fmamk_f32 v155, v155, 0x3a800000, v1
	v_mul_f32_e32 v166, 0x4b800000, v155
	v_cmp_gt_f32_e32 vcc, s22, v155
	s_nop 1
	v_cndmask_b32_e32 v155, v155, v166, vcc
	v_rsq_f32_e32 v155, v155
	v_add_co_u32_e64 v166, s[0:1], s3, v164
	v_mul_f32_e32 v164, 0x45800000, v155
	v_cndmask_b32_e32 v164, v155, v164, vcc
	v_pk_mul_f32 v[168:169], v[168:169], v[164:165] op_sel_hi:[1,0]
	v_pk_mul_f32 v[170:171], v[170:171], v[164:165] op_sel_hi:[1,0]
	v_pk_mul_f32 v[146:147], v[146:147], v[164:165] op_sel_hi:[1,0]
	v_pk_mul_f32 v[148:149], v[148:149], v[164:165] op_sel_hi:[1,0]
	v_pk_mul_f32 v[168:169], v[2:3], v[168:169]
	v_addc_co_u32_e64 v167, s[0:1], 0, v165, s[0:1]
	v_pk_mul_f32 v[150:151], v[150:151], v[164:165] op_sel_hi:[1,0]
	v_pk_mul_f32 v[152:153], v[152:153], v[164:165] op_sel_hi:[1,0]
	v_pk_mul_f32 v[172:173], v[172:173], v[164:165] op_sel_hi:[1,0]
	v_pk_mul_f32 v[174:175], v[174:175], v[164:165] op_sel_hi:[1,0]
	v_pk_mul_f32 v[170:171], v[4:5], v[170:171]
	v_pk_mul_f32 v[176:177], v[14:15], v[146:147]
	v_pk_mul_f32 v[146:147], v[16:17], v[148:149]
	v_cvt_pk_bf16_f32 v148, v168, v169
	s_waitcnt lgkmcnt(14)
	v_mul_f32_e32 v155, v67, v169
	v_mul_f32_e32 v165, v75, v169
	v_mul_f32_e32 v184, v83, v169
	s_waitcnt lgkmcnt(13)
	v_mul_f32_e32 v185, v91, v169
	v_mul_f32_e32 v186, v19, v169
	v_mul_f32_e32 v187, v23, v169
	v_mul_f32_e32 v188, v27, v169
	v_mul_f32_e32 v169, v31, v169
	v_pk_mul_f32 v[150:151], v[6:7], v[150:151]
	v_pk_mul_f32 v[152:153], v[8:9], v[152:153]
	v_pk_mul_f32 v[172:173], v[10:11], v[172:173]
	v_pk_mul_f32 v[174:175], v[12:13], v[174:175]
	v_cvt_pk_bf16_f32 v149, v170, v171
	v_fmac_f32_e32 v155, v66, v168
	v_fmac_f32_e32 v165, v74, v168
	v_fmac_f32_e32 v184, v82, v168
	v_fmac_f32_e32 v185, v90, v168
	v_fmac_f32_e32 v186, v18, v168
	v_fmac_f32_e32 v187, v22, v168
	v_fmac_f32_e32 v188, v26, v168
	v_fmac_f32_e32 v169, v30, v168
	v_cvt_pk_bf16_f32 v178, v150, v151
	v_cvt_pk_bf16_f32 v179, v152, v153
	v_cvt_pk_bf16_f32 v180, v172, v173
	v_cvt_pk_bf16_f32 v181, v174, v175
	v_cvt_pk_bf16_f32 v182, v176, v177
	v_cvt_pk_bf16_f32 v183, v146, v147
	global_store_dwordx2 v[166:167], v[148:149], off sc1
	global_store_dwordx2 v[166:167], v[178:179], off offset:512 sc1
	global_store_dwordx2 v[166:167], v[180:181], off offset:1024 sc1
	global_store_dwordx2 v[166:167], v[182:183], off offset:1536 sc1
	v_fmac_f32_e32 v155, v68, v170
	v_fmac_f32_e32 v165, v76, v170
	v_fmac_f32_e32 v184, v84, v170
	v_fmac_f32_e32 v185, v92, v170
	v_fmac_f32_e32 v186, v20, v170
	v_fmac_f32_e32 v187, v24, v170
	v_fmac_f32_e32 v188, v28, v170
	v_fmac_f32_e32 v169, v32, v170
	v_mul_f32_e32 v148, v71, v151
	v_fmac_f32_e32 v155, v69, v171
	v_fmac_f32_e32 v165, v77, v171
	v_fmac_f32_e32 v184, v85, v171
	v_fmac_f32_e32 v185, v93, v171
	v_fmac_f32_e32 v186, v21, v171
	v_fmac_f32_e32 v187, v25, v171
	v_fmac_f32_e32 v188, v29, v171
	v_fmac_f32_e32 v169, v33, v171
	v_fmac_f32_e32 v148, v70, v150
	v_mul_f32_e32 v149, v79, v151
	v_mul_f32_e32 v166, v87, v151
	s_waitcnt lgkmcnt(12)
; #define LAS __attribute__((address_space(3)))
; template <int MODE  > ...
;     ...
;             if (MODE == 1) {
; #pragma unroll
;                 for (int h = 0; h < 8; ++h) {
;                     typedef float f4v __attribute__((ext_vector_type(4)));
;                     const f4v wv = *(const LAS f4v*)(ldsb + h * 16384 + 8448 + (256 * j + 4 * lane) * 4);
;                     dacc[h] += y[j][0] * wv.x + y[j][1] * wv.y + y[j][2] * wv.z + y[j][3] * wv.w;
;                 }
	v_mul_f32_e32 v167, v95, v151
	v_mul_f32_e32 v168, v35, v151
	v_mul_f32_e32 v170, v39, v151
	v_mul_f32_e32 v171, v43, v151
	v_mul_f32_e32 v151, v47, v151
	v_fmac_f32_e32 v149, v78, v150
	v_fmac_f32_e32 v166, v86, v150
	v_fmac_f32_e32 v167, v94, v150
	v_fmac_f32_e32 v168, v34, v150
	v_fmac_f32_e32 v170, v38, v150
	v_fmac_f32_e32 v171, v42, v150
	v_fmac_f32_e32 v151, v46, v150
	v_fmac_f32_e32 v148, v72, v152
	v_fmac_f32_e32 v148, v73, v153
	v_fmac_f32_e32 v149, v80, v152
	v_fmac_f32_e32 v166, v88, v152
	v_fmac_f32_e32 v167, v96, v152
	v_fmac_f32_e32 v168, v36, v152
	v_fmac_f32_e32 v170, v40, v152
	v_fmac_f32_e32 v171, v44, v152
	v_fmac_f32_e32 v151, v48, v152
	v_add_f32_e32 v155, 0, v155
	v_fmac_f32_e32 v149, v81, v153
	v_fmac_f32_e32 v166, v89, v153
	v_fmac_f32_e32 v167, v97, v153
	v_fmac_f32_e32 v168, v37, v153
	v_fmac_f32_e32 v170, v41, v153
	v_fmac_f32_e32 v171, v45, v153
	v_fmac_f32_e32 v151, v49, v153
	s_waitcnt lgkmcnt(11)
	v_mul_f32_e32 v150, v99, v173
	s_waitcnt lgkmcnt(7)
	v_mul_f32_e32 v153, v115, v173
	v_mul_f32_e32 v179, v51, v173
	v_add_f32_e32 v148, v148, v155
	v_add_f32_e32 v155, 0, v165
	v_fmac_f32_e32 v150, v98, v172
	v_fmac_f32_e32 v153, v114, v172
	v_fmac_f32_e32 v179, v50, v172
	v_add_f32_e32 v149, v149, v155
	v_add_f32_e32 v155, 0, v184
	v_fmac_f32_e32 v150, v100, v174
	v_fmac_f32_e32 v153, v116, v174
	v_fmac_f32_e32 v179, v52, v174
	v_add_f32_e32 v155, v166, v155
	v_add_f32_e32 v166, 0, v186
	v_fmac_f32_e32 v150, v101, v175
	v_fmac_f32_e32 v153, v117, v175
	v_fmac_f32_e32 v179, v53, v175
	v_add_f32_e32 v166, v168, v166
	v_add_f32_e32 v148, v150, v148
	v_add_f32_e32 v150, v153, v155
	v_add_f32_e32 v153, v179, v166
	v_mul_f32_e32 v166, v103, v177
	v_fmac_f32_e32 v166, v102, v176
	v_fmac_f32_e32 v166, v104, v146
	v_mul_f32_e32 v152, v107, v173
	v_fmac_f32_e32 v166, v105, v147
	v_fmac_f32_e32 v152, v106, v172
	v_add_f32_e32 v148, v166, v148
	v_mul_f32_e32 v166, v111, v177
	v_fmac_f32_e32 v152, v108, v174
	v_fmac_f32_e32 v166, v110, v176
	v_fmac_f32_e32 v152, v109, v175
	v_fmac_f32_e32 v166, v112, v146
	v_add_f32_e32 v149, v152, v149
	v_fmac_f32_e32 v166, v113, v147
	v_add_f32_e32 v149, v166, v149
	s_waitcnt lgkmcnt(6)
	v_mul_f32_e32 v166, v119, v177
	v_fmac_f32_e32 v166, v118, v176
	v_fmac_f32_e32 v166, v120, v146
	s_waitcnt lgkmcnt(5)
	v_mul_f32_e32 v178, v123, v173
	v_fmac_f32_e32 v166, v121, v147
	v_fmac_f32_e32 v178, v122, v172
	v_add_f32_e32 v150, v166, v150
	s_waitcnt lgkmcnt(4)
	v_mul_f32_e32 v166, v127, v177
	v_fmac_f32_e32 v178, v124, v174
	v_add_f32_e32 v165, 0, v185
	v_fmac_f32_e32 v166, v126, v176
	v_fmac_f32_e32 v178, v125, v175
	v_add_f32_e32 v165, v167, v165
	v_fmac_f32_e32 v166, v128, v146
	v_add_f32_e32 v152, v178, v165
	v_fmac_f32_e32 v166, v129, v147
	v_add_f32_e32 v152, v166, v152
	s_waitcnt lgkmcnt(3)
	v_mul_f32_e32 v166, v131, v177
	v_fmac_f32_e32 v166, v130, v176
	v_fmac_f32_e32 v166, v132, v146
	v_mul_f32_e32 v180, v55, v173
	v_fmac_f32_e32 v166, v133, v147
	v_fmac_f32_e32 v180, v54, v172
	v_add_f32_e32 v153, v166, v153
	s_waitcnt lgkmcnt(2)
	v_mul_f32_e32 v166, v135, v177
	v_fmac_f32_e32 v180, v56, v174
	v_add_f32_e32 v167, 0, v187
	v_fmac_f32_e32 v166, v134, v176
	v_fmac_f32_e32 v180, v57, v175
	v_add_f32_e32 v167, v170, v167
	v_fmac_f32_e32 v166, v136, v146
	v_mul_f32_e32 v181, v59, v173
	v_add_f32_e32 v155, v180, v167
	v_fmac_f32_e32 v166, v137, v147
	v_fmac_f32_e32 v181, v58, v172
	v_add_f32_e32 v155, v166, v155
	s_waitcnt lgkmcnt(1)
	v_mul_f32_e32 v166, v139, v177
	v_fmac_f32_e32 v181, v60, v174
	v_add_f32_e32 v168, 0, v188
	v_fmac_f32_e32 v166, v138, v176
	v_fmac_f32_e32 v181, v61, v175
	v_add_f32_e32 v168, v171, v168
	v_fmac_f32_e32 v166, v140, v146
	v_add_f32_e32 v165, v181, v168
	v_fmac_f32_e32 v166, v141, v147
	v_add_f32_e32 v165, v166, v165
	s_waitcnt lgkmcnt(0)
; template <int MODE  > ...
;     ...
;         if (MODE == 1) {
; #pragma unroll
;             for (int h = 0; h < 8; ++h) dacc[h] = wave_sum(dacc[h]);
;             if (lane == 0) { float4* dp = (float4*)(dtraw + (size_t)row * 8); dp[0] = make_float4(dacc[0], dacc[1], dacc[2], dacc[3]); dp[1] = make_float4(dacc[4], dacc[5], dacc[6], dacc[7]); xs[row] = 1.f / r; }
;         }
	v_mul_f32_e32 v166, v143, v177
	v_fmac_f32_e32 v166, v142, v176
	v_fmac_f32_e32 v166, v144, v146
	v_fmac_f32_e32 v166, v145, v147
	v_add_f32_dpp v147, v148, v148 quad_perm:[1,0,3,2] row_mask:0xf bank_mask:0xf bound_ctrl:1
	v_mul_f32_e32 v173, v63, v173
	v_fmac_f32_e32 v173, v62, v172
	v_add_f32_dpp v147, v147, v147 quad_perm:[2,3,0,1] row_mask:0xf bank_mask:0xf bound_ctrl:1
	v_fmac_f32_e32 v173, v64, v174
	v_add_f32_e32 v169, 0, v169
	v_add_f32_dpp v147, v147, v147 row_half_mirror row_mask:0xf bank_mask:0xf bound_ctrl:1
	v_fmac_f32_e32 v173, v65, v175
	v_add_f32_e32 v151, v151, v169
	v_add_f32_dpp v147, v147, v147 row_mirror row_mask:0xf bank_mask:0xf bound_ctrl:1
	v_add_f32_e32 v151, v173, v151
	v_readlane_b32 s0, v147, 0
	v_readlane_b32 s42, v147, 16
	v_readlane_b32 s22, v147, 32
	v_readlane_b32 s41, v147, 48
	v_add_f32_dpp v147, v149, v149 quad_perm:[1,0,3,2] row_mask:0xf bank_mask:0xf bound_ctrl:1
	v_add_f32_e32 v146, v166, v151
	s_nop 0
	v_add_f32_dpp v147, v147, v147 quad_perm:[2,3,0,1] row_mask:0xf bank_mask:0xf bound_ctrl:1
	v_add_f32_dpp v146, v146, v146 quad_perm:[1,0,3,2] row_mask:0xf bank_mask:0xf bound_ctrl:1
	s_nop 0
	v_add_f32_dpp v147, v147, v147 row_half_mirror row_mask:0xf bank_mask:0xf bound_ctrl:1
	v_add_f32_dpp v146, v146, v146 quad_perm:[2,3,0,1] row_mask:0xf bank_mask:0xf bound_ctrl:1
	s_nop 0
	v_add_f32_dpp v147, v147, v147 row_mirror row_mask:0xf bank_mask:0xf bound_ctrl:1
	v_add_f32_dpp v146, v146, v146 row_half_mirror row_mask:0xf bank_mask:0xf bound_ctrl:1
	v_readlane_b32 s1, v147, 0
	v_readlane_b32 s44, v147, 16
	v_readlane_b32 s23, v147, 32
	v_readlane_b32 s43, v147, 48
	v_add_f32_dpp v147, v150, v150 quad_perm:[1,0,3,2] row_mask:0xf bank_mask:0xf bound_ctrl:1
	v_add_f32_dpp v146, v146, v146 row_mirror row_mask:0xf bank_mask:0xf bound_ctrl:1
	s_nop 0
	v_add_f32_dpp v147, v147, v147 quad_perm:[2,3,0,1] row_mask:0xf bank_mask:0xf bound_ctrl:1
	v_readlane_b32 s39, v146, 0
	v_readlane_b32 s70, v146, 16
	v_add_f32_dpp v147, v147, v147 row_half_mirror row_mask:0xf bank_mask:0xf bound_ctrl:1
	v_readlane_b32 s37, v146, 32
	v_readlane_b32 s69, v146, 48
	v_add_f32_dpp v147, v147, v147 row_mirror row_mask:0xf bank_mask:0xf bound_ctrl:1
	s_nop 0
	v_readlane_b32 s24, v147, 0
	v_readlane_b32 s46, v147, 16
	v_readlane_b32 s28, v147, 32
	v_readlane_b32 s45, v147, 48
	v_add_f32_dpp v147, v152, v152 quad_perm:[1,0,3,2] row_mask:0xf bank_mask:0xf bound_ctrl:1
	s_nop 1
	v_add_f32_dpp v147, v147, v147 quad_perm:[2,3,0,1] row_mask:0xf bank_mask:0xf bound_ctrl:1
	s_nop 1
	v_add_f32_dpp v147, v147, v147 row_half_mirror row_mask:0xf bank_mask:0xf bound_ctrl:1
	s_nop 1
	v_add_f32_dpp v147, v147, v147 row_mirror row_mask:0xf bank_mask:0xf bound_ctrl:1
	s_nop 0
	v_readlane_b32 s25, v147, 0
	v_readlane_b32 s48, v147, 16
	v_readlane_b32 s29, v147, 32
	v_readlane_b32 s47, v147, 48
	v_add_f32_dpp v147, v153, v153 quad_perm:[1,0,3,2] row_mask:0xf bank_mask:0xf bound_ctrl:1
	s_nop 1
	v_add_f32_dpp v147, v147, v147 quad_perm:[2,3,0,1] row_mask:0xf bank_mask:0xf bound_ctrl:1
	s_nop 1
	v_add_f32_dpp v147, v147, v147 row_half_mirror row_mask:0xf bank_mask:0xf bound_ctrl:1
	s_nop 1
	v_add_f32_dpp v147, v147, v147 row_mirror row_mask:0xf bank_mask:0xf bound_ctrl:1
	s_nop 0
	v_readlane_b32 s30, v147, 0
	v_readlane_b32 s50, v147, 16
	v_readlane_b32 s34, v147, 32
	v_readlane_b32 s49, v147, 48
	v_add_f32_dpp v147, v155, v155 quad_perm:[1,0,3,2] row_mask:0xf bank_mask:0xf bound_ctrl:1
	s_nop 1
	v_add_f32_dpp v147, v147, v147 quad_perm:[2,3,0,1] row_mask:0xf bank_mask:0xf bound_ctrl:1
	s_nop 1
	v_add_f32_dpp v147, v147, v147 row_half_mirror row_mask:0xf bank_mask:0xf bound_ctrl:1
	s_nop 1
	v_add_f32_dpp v147, v147, v147 row_mirror row_mask:0xf bank_mask:0xf bound_ctrl:1
	s_nop 0
	v_readlane_b32 s31, v147, 0
	v_readlane_b32 s64, v147, 16
	v_readlane_b32 s35, v147, 32
	v_readlane_b32 s51, v147, 48
	v_add_f32_dpp v147, v165, v165 quad_perm:[1,0,3,2] row_mask:0xf bank_mask:0xf bound_ctrl:1
	s_nop 1
	v_add_f32_dpp v147, v147, v147 quad_perm:[2,3,0,1] row_mask:0xf bank_mask:0xf bound_ctrl:1
	s_nop 1
	v_add_f32_dpp v147, v147, v147 row_half_mirror row_mask:0xf bank_mask:0xf bound_ctrl:1
	s_nop 1
	v_add_f32_dpp v147, v147, v147 row_mirror row_mask:0xf bank_mask:0xf bound_ctrl:1
	s_nop 0
	v_readlane_b32 s38, v147, 0
	v_readlane_b32 s68, v147, 16
	v_readlane_b32 s36, v147, 32
	v_readlane_b32 s65, v147, 48
	s_and_saveexec_b64 s[26:27], s[4:5]
	s_cbranch_execz .LBB0_28
	v_mov_b32_e32 v148, s46
	v_mov_b32_e32 v149, s48
	v_mov_b32_e32 v170, s45
	v_mov_b32_e32 v171, s47
	v_mov_b32_e32 v146, s42
	v_mov_b32_e32 v147, s44
	v_mov_b32_e32 v172, s41
	v_mov_b32_e32 v173, s43
	v_lshl_add_u64 v[174:175], s[90:91], 0, v[162:163]
	v_pk_add_f32 v[148:149], s[24:25], v[148:149]
	v_pk_add_f32 v[170:171], s[28:29], v[170:171]
	v_pk_add_f32 v[146:147], s[0:1], v[146:147]
	v_pk_add_f32 v[172:173], s[22:23], v[172:173]
	v_pk_add_f32 v[148:149], v[148:149], v[170:171]
	v_add_co_u32_e32 v170, vcc, s9, v174
	v_div_scale_f32 v155, s[0:1], v164, v164, 1.0
	v_mov_b32_e32 v166, s50
	v_mov_b32_e32 v167, s64
	v_mov_b32_e32 v168, s49
	v_mov_b32_e32 v169, s51
	v_pk_add_f32 v[146:147], v[146:147], v[172:173]
	v_addc_co_u32_e32 v171, vcc, 0, v175, vcc
	v_rcp_f32_e32 v165, v155
	v_mov_b32_e32 v150, s68
	v_mov_b32_e32 v151, s70
	v_mov_b32_e32 v152, s65
	v_mov_b32_e32 v153, s69
	global_store_dwordx4 v[170:171], v[146:149], off sc1
	s_nop 1
	v_pk_add_f32 v[146:147], s[30:31], v[166:167]
	v_pk_add_f32 v[148:149], s[34:35], v[168:169]
	s_nop 0
	v_pk_add_f32 v[146:147], v[146:147], v[148:149]
	v_pk_add_f32 v[148:149], s[38:39], v[150:151]
	v_pk_add_f32 v[150:151], s[36:37], v[152:153]
	s_nop 0
	v_pk_add_f32 v[148:149], v[148:149], v[150:151]
	global_store_dwordx4 v[170:171], v[146:149], off offset:16 sc1
	s_nop 1
	v_fma_f32 v146, -v155, v165, 1.0
	v_fmac_f32_e32 v165, v146, v165
	v_div_scale_f32 v146, vcc, 1.0, v164, 1.0
	v_mul_f32_e32 v147, v146, v165
	v_fma_f32 v148, -v155, v147, v146
	v_fmac_f32_e32 v147, v148, v165
	v_fma_f32 v146, -v155, v147, v146
	v_div_fmas_f32 v146, v146, v165, v147
	v_div_fixup_f32 v148, v146, v164, 1.0
	v_lshl_add_u64 v[146:147], s[90:91], 0, v[156:157]
	global_store_dword v[146:147], v148, off sc1
	s_branch .LBB0_28
